# attention softmax: cross-half row max via v_permlane32_swap instead of the ds_bpermute LDS round trip (counted lgkmcnt for the V fragments afterwards)
# speedup vs baseline: 1.0035x; 1.0017x over previous
.Latt3_A_loop:
	v_add_u32_e32 v209, s70, v215
	v_add_u32_e32 v205, s70, v216
	ds_read_b128 v[226:229], v209
	ds_read_b128 v[236:239], v209 offset:12800
	ds_read_b128 v[240:243], v209 offset:32
	ds_read_b128 v[244:247], v209 offset:12832
	ds_read_b128 v[248:251], v209 offset:64
	ds_read_b128 v[210:213], v209 offset:12864
	s_waitcnt lgkmcnt(5)
	v_mfma_f32_32x32x16_bf16 v[82:97], v[226:229], v[126:129], 0
	ds_read_b128 v[226:229], v209 offset:96
	s_waitcnt lgkmcnt(5)
	v_mfma_f32_32x32x16_bf16 v[66:81], v[236:239], v[126:129], 0
	ds_read_b128 v[236:239], v209 offset:12896
	s_waitcnt lgkmcnt(5)
	v_mfma_f32_32x32x16_bf16 v[82:97], v[240:243], v[142:145], v[82:97]
	ds_read_b128 v[240:243], v209 offset:128
	s_waitcnt lgkmcnt(5)
	v_mfma_f32_32x32x16_bf16 v[66:81], v[244:247], v[142:145], v[66:81]
	ds_read_b128 v[244:247], v209 offset:12928
	s_waitcnt lgkmcnt(5)
	v_mfma_f32_32x32x16_bf16 v[82:97], v[248:251], v[146:149], v[82:97]
	ds_read_b128 v[248:251], v209 offset:160
	s_waitcnt lgkmcnt(5)
	v_mfma_f32_32x32x16_bf16 v[66:81], v[210:213], v[146:149], v[66:81]
	ds_read_b128 v[210:213], v209 offset:12960
	s_waitcnt lgkmcnt(5)
	v_mfma_f32_32x32x16_bf16 v[82:97], v[226:229], v[150:153], v[82:97]
	ds_read_b128 v[226:229], v209 offset:192
	s_waitcnt lgkmcnt(5)
	v_mfma_f32_32x32x16_bf16 v[66:81], v[236:239], v[150:153], v[66:81]
	ds_read_b128 v[236:239], v209 offset:12992
	s_waitcnt lgkmcnt(5)
	v_mfma_f32_32x32x16_bf16 v[82:97], v[240:243], v[154:157], v[82:97]
	ds_read_b128 v[240:243], v209 offset:224
	s_waitcnt lgkmcnt(5)
	v_mfma_f32_32x32x16_bf16 v[66:81], v[244:247], v[154:157], v[66:81]
	ds_read_b128 v[244:247], v209 offset:13024
	s_waitcnt lgkmcnt(5)
	v_mfma_f32_32x32x16_bf16 v[82:97], v[248:251], v[158:161], v[82:97]
	ds_read_b128 v[248:251], v209 offset:256
	s_waitcnt lgkmcnt(5)
	v_mfma_f32_32x32x16_bf16 v[66:81], v[210:213], v[158:161], v[66:81]
	ds_read_b128 v[210:213], v209 offset:13056
	s_waitcnt lgkmcnt(5)
	v_mfma_f32_32x32x16_bf16 v[82:97], v[226:229], v[162:165], v[82:97]
	ds_read_b128 v[226:229], v209 offset:288
	s_waitcnt lgkmcnt(5)
	v_mfma_f32_32x32x16_bf16 v[66:81], v[236:239], v[162:165], v[66:81]
	ds_read_b128 v[236:239], v209 offset:13088
	s_waitcnt lgkmcnt(5)
	v_mfma_f32_32x32x16_bf16 v[82:97], v[240:243], v[166:169], v[82:97]
	ds_read_b128 v[240:243], v209 offset:320
	s_waitcnt lgkmcnt(5)
	v_mfma_f32_32x32x16_bf16 v[66:81], v[244:247], v[166:169], v[66:81]
	ds_read_b128 v[244:247], v209 offset:13120
	s_waitcnt lgkmcnt(5)
	v_mfma_f32_32x32x16_bf16 v[82:97], v[248:251], v[170:173], v[82:97]
	ds_read_b128 v[248:251], v209 offset:352
	s_waitcnt lgkmcnt(5)
	v_mfma_f32_32x32x16_bf16 v[66:81], v[210:213], v[170:173], v[66:81]
	ds_read_b128 v[210:213], v209 offset:13152
	s_waitcnt lgkmcnt(5)
	v_mfma_f32_32x32x16_bf16 v[82:97], v[226:229], v[174:177], v[82:97]
	s_waitcnt lgkmcnt(4)
	v_mfma_f32_32x32x16_bf16 v[66:81], v[236:239], v[174:177], v[66:81]
	s_waitcnt lgkmcnt(3)
	v_mfma_f32_32x32x16_bf16 v[82:97], v[240:243], v[178:181], v[82:97]
	s_waitcnt lgkmcnt(2)
	v_mfma_f32_32x32x16_bf16 v[66:81], v[244:247], v[178:181], v[66:81]
	s_waitcnt lgkmcnt(1)
	v_mfma_f32_32x32x16_bf16 v[82:97], v[248:251], v[182:185], v[82:97]
	s_waitcnt lgkmcnt(0)
	v_mfma_f32_32x32x16_bf16 v[66:81], v[210:213], v[182:185], v[66:81]
	s_setprio 2
	ds_read_b128 v[236:239], v205 offset:25600
	ds_read_b128 v[240:243], v205 offset:30208
	ds_read_b128 v[244:247], v205 offset:34816
	ds_read_b128 v[248:251], v205 offset:39424
	ds_read_b128 v[210:213], v205 offset:25632
	s_nop 4
	v_max_f32_e32 v186, v83, v83
	v_max_f32_e32 v187, v82, v82
	v_max_f32_e32 v186, v187, v186
	v_max3_f32 v186, v186, v84, v85
	v_max3_f32 v186, v186, v86, v87
	v_max3_f32 v186, v186, v88, v89
	v_max3_f32 v186, v186, v90, v91
	v_max3_f32 v186, v186, v92, v93
	v_max3_f32 v186, v186, v94, v95
	v_max3_f32 v186, v186, v96, v97
	v_max3_f32 v186, v186, v66, v67
	v_max3_f32 v186, v186, v68, v69
	v_max3_f32 v186, v186, v70, v71
	v_max3_f32 v186, v186, v72, v73
	v_max3_f32 v186, v186, v74, v75
	v_max3_f32 v186, v186, v76, v77
	v_max3_f32 v186, v186, v78, v79
	v_max3_f32 v186, v186, v80, v81
	v_mov_b32_e32 v187, v186
	s_nop 1
	v_permlane32_swap_b32_e32 v186, v187
	v_max_f32_e32 v187, v186, v187
	v_add_f32_e32 v186, 0x41380000, v223
	v_cmp_gt_f32_e32 vcc, v187, v186
	s_cbranch_vccz .Latt3_nr_5
	v_max_f32_e32 v186, v187, v187
	v_max_f32_e32 v187, v223, v223
	v_max_f32_e32 v187, v187, v186
	v_sub_f32_e32 v186, v223, v187
	v_exp_f32_e32 v186, v186
	v_mov_b32_e32 v223, v187
	v_pk_mul_f32 v[64:65], v[64:65], v[186:187] op_sel_hi:[1,0]
	v_pk_mul_f32 v[62:63], v[62:63], v[186:187] op_sel_hi:[1,0]
	v_pk_mul_f32 v[60:61], v[60:61], v[186:187] op_sel_hi:[1,0]
	v_pk_mul_f32 v[58:59], v[58:59], v[186:187] op_sel_hi:[1,0]
	v_pk_mul_f32 v[56:57], v[56:57], v[186:187] op_sel_hi:[1,0]
	v_pk_mul_f32 v[54:55], v[54:55], v[186:187] op_sel_hi:[1,0]
	v_pk_mul_f32 v[52:53], v[52:53], v[186:187] op_sel_hi:[1,0]
	v_pk_mul_f32 v[50:51], v[50:51], v[186:187] op_sel_hi:[1,0]
	v_pk_mul_f32 v[48:49], v[48:49], v[186:187] op_sel_hi:[1,0]
	v_pk_mul_f32 v[46:47], v[46:47], v[186:187] op_sel_hi:[1,0]
	v_pk_mul_f32 v[44:45], v[44:45], v[186:187] op_sel_hi:[1,0]
	v_pk_mul_f32 v[42:43], v[42:43], v[186:187] op_sel_hi:[1,0]
	v_pk_mul_f32 v[40:41], v[40:41], v[186:187] op_sel_hi:[1,0]
	v_pk_mul_f32 v[38:39], v[38:39], v[186:187] op_sel_hi:[1,0]
	v_pk_mul_f32 v[36:37], v[36:37], v[186:187] op_sel_hi:[1,0]
	v_pk_mul_f32 v[34:35], v[34:35], v[186:187] op_sel_hi:[1,0]
	v_pk_mul_f32 v[32:33], v[32:33], v[186:187] op_sel_hi:[1,0]
	v_pk_mul_f32 v[30:31], v[30:31], v[186:187] op_sel_hi:[1,0]
	v_pk_mul_f32 v[28:29], v[28:29], v[186:187] op_sel_hi:[1,0]
	v_pk_mul_f32 v[26:27], v[26:27], v[186:187] op_sel_hi:[1,0]
	v_pk_mul_f32 v[24:25], v[24:25], v[186:187] op_sel_hi:[1,0]
	v_pk_mul_f32 v[22:23], v[22:23], v[186:187] op_sel_hi:[1,0]
	v_pk_mul_f32 v[20:21], v[20:21], v[186:187] op_sel_hi:[1,0]
	v_pk_mul_f32 v[18:19], v[18:19], v[186:187] op_sel_hi:[1,0]
	v_pk_mul_f32 v[16:17], v[16:17], v[186:187] op_sel_hi:[1,0]
	v_pk_mul_f32 v[14:15], v[14:15], v[186:187] op_sel_hi:[1,0]
	v_pk_mul_f32 v[12:13], v[12:13], v[186:187] op_sel_hi:[1,0]
	v_pk_mul_f32 v[10:11], v[10:11], v[186:187] op_sel_hi:[1,0]
	v_pk_mul_f32 v[8:9], v[8:9], v[186:187] op_sel_hi:[1,0]
	v_pk_mul_f32 v[6:7], v[6:7], v[186:187] op_sel_hi:[1,0]
	v_pk_mul_f32 v[4:5], v[4:5], v[186:187] op_sel_hi:[1,0]
	v_pk_mul_f32 v[2:3], v[2:3], v[186:187] op_sel_hi:[1,0]
	v_mul_f32_e32 v224, v224, v186
.Latt3_nr_5:
	v_sub_f32_e32 v82, v82, v223
	v_sub_f32_e32 v83, v83, v223
	v_sub_f32_e32 v84, v84, v223
	v_sub_f32_e32 v85, v85, v223
	v_exp_f32_e32 v82, v82
	v_exp_f32_e32 v83, v83
	v_exp_f32_e32 v84, v84
	v_exp_f32_e32 v85, v85
	v_sub_f32_e32 v86, v86, v223
	v_sub_f32_e32 v87, v87, v223
	v_sub_f32_e32 v88, v88, v223
	v_sub_f32_e32 v89, v89, v223
	v_exp_f32_e32 v86, v86
	v_exp_f32_e32 v87, v87
	v_exp_f32_e32 v88, v88
	v_exp_f32_e32 v89, v89
	v_cvt_pk_bf16_f32 v226, v82, v83
	v_cvt_pk_bf16_f32 v227, v84, v85
	v_cvt_pk_bf16_f32 v228, v86, v87
	v_cvt_pk_bf16_f32 v229, v88, v89
	s_nop 1
	s_waitcnt lgkmcnt(4)
	v_mfma_f32_32x32x16_bf16 v[50:65], v[236:239], v[226:229], v[50:65]
	ds_read_b128 v[236:239], v205 offset:30240
	v_sub_f32_e32 v90, v90, v223
	v_sub_f32_e32 v91, v91, v223
	v_sub_f32_e32 v92, v92, v223
	v_sub_f32_e32 v93, v93, v223
	v_exp_f32_e32 v90, v90
	v_exp_f32_e32 v91, v91
	s_waitcnt lgkmcnt(4)
	v_mfma_f32_32x32x16_bf16 v[34:49], v[240:243], v[226:229], v[34:49]
	ds_read_b128 v[240:243], v205 offset:34848
	v_exp_f32_e32 v92, v92
	v_exp_f32_e32 v93, v93
	v_sub_f32_e32 v94, v94, v223
	v_sub_f32_e32 v95, v95, v223
	v_sub_f32_e32 v96, v96, v223
	v_sub_f32_e32 v97, v97, v223
	s_waitcnt lgkmcnt(4)
	v_mfma_f32_32x32x16_bf16 v[18:33], v[244:247], v[226:229], v[18:33]
	ds_read_b128 v[244:247], v205 offset:39456
	v_exp_f32_e32 v94, v94
	v_exp_f32_e32 v95, v95
	v_exp_f32_e32 v96, v96
	v_exp_f32_e32 v97, v97
	v_add_f32_e32 v186, 0, v82
	v_add_f32_e32 v187, 0, v86
	s_waitcnt lgkmcnt(4)
	v_mfma_f32_32x32x16_bf16 v[2:17], v[248:251], v[226:229], v[2:17]
	ds_read_b128 v[248:251], v205 offset:25664
	v_add_f32_e32 v186, v83, v186
	v_add_f32_e32 v187, v87, v187
	v_add_f32_e32 v186, v84, v186
	v_add_f32_e32 v187, v88, v187
	v_add_f32_e32 v186, v85, v186
	v_add_f32_e32 v187, v89, v187
	v_cvt_pk_bf16_f32 v226, v90, v91
	v_cvt_pk_bf16_f32 v227, v92, v93
	v_cvt_pk_bf16_f32 v228, v94, v95
	v_cvt_pk_bf16_f32 v229, v96, v97
	s_nop 1
	s_waitcnt lgkmcnt(4)
	v_mfma_f32_32x32x16_bf16 v[50:65], v[210:213], v[226:229], v[50:65]
	ds_read_b128 v[210:213], v205 offset:30272
	v_sub_f32_e32 v66, v66, v223
	v_sub_f32_e32 v67, v67, v223
	v_sub_f32_e32 v68, v68, v223
	v_sub_f32_e32 v69, v69, v223
	v_exp_f32_e32 v66, v66
	v_exp_f32_e32 v67, v67
	s_waitcnt lgkmcnt(4)
	v_mfma_f32_32x32x16_bf16 v[34:49], v[236:239], v[226:229], v[34:49]
	ds_read_b128 v[236:239], v205 offset:34880
	v_exp_f32_e32 v68, v68
	v_exp_f32_e32 v69, v69
	v_sub_f32_e32 v70, v70, v223
	v_sub_f32_e32 v71, v71, v223
	v_sub_f32_e32 v72, v72, v223
	v_sub_f32_e32 v73, v73, v223
	s_waitcnt lgkmcnt(4)
	v_mfma_f32_32x32x16_bf16 v[18:33], v[240:243], v[226:229], v[18:33]
	ds_read_b128 v[240:243], v205 offset:39488
	v_exp_f32_e32 v70, v70
	v_exp_f32_e32 v71, v71
	v_exp_f32_e32 v72, v72
	v_exp_f32_e32 v73, v73
	v_add_f32_e32 v186, v90, v186
	v_add_f32_e32 v187, v94, v187
	s_waitcnt lgkmcnt(4)
	v_mfma_f32_32x32x16_bf16 v[2:17], v[244:247], v[226:229], v[2:17]
	ds_read_b128 v[244:247], v205 offset:25696
	v_add_f32_e32 v186, v91, v186
	v_add_f32_e32 v187, v95, v187
	v_add_f32_e32 v186, v92, v186
	v_add_f32_e32 v187, v96, v187
	v_add_f32_e32 v186, v93, v186
	v_add_f32_e32 v187, v97, v187
	v_cvt_pk_bf16_f32 v226, v66, v67
	v_cvt_pk_bf16_f32 v227, v68, v69
	v_cvt_pk_bf16_f32 v228, v70, v71
	v_cvt_pk_bf16_f32 v229, v72, v73
	s_nop 1
	s_waitcnt lgkmcnt(4)
	v_mfma_f32_32x32x16_bf16 v[50:65], v[248:251], v[226:229], v[50:65]
	ds_read_b128 v[248:251], v205 offset:30304
	v_sub_f32_e32 v74, v74, v223
	v_sub_f32_e32 v75, v75, v223
	v_sub_f32_e32 v76, v76, v223
	v_sub_f32_e32 v77, v77, v223
	v_exp_f32_e32 v74, v74
	v_exp_f32_e32 v75, v75
	s_waitcnt lgkmcnt(4)
	v_mfma_f32_32x32x16_bf16 v[34:49], v[210:213], v[226:229], v[34:49]
	ds_read_b128 v[210:213], v205 offset:34912
	v_exp_f32_e32 v76, v76
	v_exp_f32_e32 v77, v77
	v_sub_f32_e32 v78, v78, v223
	v_sub_f32_e32 v79, v79, v223
	v_sub_f32_e32 v80, v80, v223
	v_sub_f32_e32 v81, v81, v223
	s_waitcnt lgkmcnt(4)
	v_mfma_f32_32x32x16_bf16 v[18:33], v[236:239], v[226:229], v[18:33]
	ds_read_b128 v[236:239], v205 offset:39520
	v_exp_f32_e32 v78, v78
	v_exp_f32_e32 v79, v79
	v_exp_f32_e32 v80, v80
	v_exp_f32_e32 v81, v81
	v_add_f32_e32 v186, v66, v186
	v_add_f32_e32 v187, v70, v187
	s_waitcnt lgkmcnt(4)
	v_mfma_f32_32x32x16_bf16 v[2:17], v[240:243], v[226:229], v[2:17]
	v_add_f32_e32 v186, v67, v186
	v_add_f32_e32 v187, v71, v187
	v_add_f32_e32 v186, v68, v186
	v_add_f32_e32 v187, v72, v187
	v_add_f32_e32 v186, v69, v186
	v_add_f32_e32 v187, v73, v187
	v_cvt_pk_bf16_f32 v226, v74, v75
	v_cvt_pk_bf16_f32 v227, v76, v77
	v_cvt_pk_bf16_f32 v228, v78, v79
	v_cvt_pk_bf16_f32 v229, v80, v81
	s_nop 1
	s_waitcnt lgkmcnt(3)
	v_mfma_f32_32x32x16_bf16 v[50:65], v[244:247], v[226:229], v[50:65]
	v_add_f32_e32 v186, v74, v186
	v_add_f32_e32 v187, v78, v187
	s_waitcnt lgkmcnt(2)
	v_mfma_f32_32x32x16_bf16 v[34:49], v[248:251], v[226:229], v[34:49]
	v_add_f32_e32 v186, v75, v186
	v_add_f32_e32 v187, v79, v187
	s_waitcnt lgkmcnt(1)
	v_mfma_f32_32x32x16_bf16 v[18:33], v[210:213], v[226:229], v[18:33]
	v_add_f32_e32 v186, v76, v186
	v_add_f32_e32 v187, v80, v187
	s_waitcnt lgkmcnt(0)
	s_barrier
	v_mfma_f32_32x32x16_bf16 v[2:17], v[236:239], v[226:229], v[2:17]
	v_add_f32_e32 v186, v77, v186
	v_add_f32_e32 v187, v81, v187
	v_add_f32_e32 v186, v186, v187
	v_add_f32_e32 v225, v224, v186
	s_setprio 0
	s_add_i32 s13, s11, 2
	s_cmp_ge_u32 s13, s5
	s_cbranch_scc1 .Latt3_wskip_6
	v_add_u32_e32 v206, s72, v219
	v_add_u32_e32 v208, s72, v220
	v_add_u32_e32 v186, s72, v221
	v_add_u32_e32 v187, s72, v222
	s_add_i32 s13, s11, 3
	s_cmp_ge_u32 s13, s5
	s_cbranch_scc1 .Latt3_wtail_7
	s_waitcnt vmcnt(9)
	ds_write_b128 v206, v[118:121]
	s_waitcnt vmcnt(8)
	ds_write_b128 v208, v[122:125]
	s_waitcnt vmcnt(7)
	ds_write_b128 v186, v[130:133]
	s_waitcnt vmcnt(6)
	ds_write_b128 v187, v[134:137] offset:25600
	s_waitcnt vmcnt(5)
	ds_write_b128 v187, v[138:141] offset:34816
	s_branch .Latt3_wld_8

.Latt3_wdone_9:
.Latt3_wskip_6:
	s_mov_b32 s13, s70
	s_mov_b32 s70, s71
	s_mov_b32 s71, s72
	s_mov_b32 s72, s13
	s_add_i32 s11, s11, 1
	v_add_u32_e32 v209, s70, v215
	v_add_u32_e32 v205, s70, v216
	ds_read_b128 v[226:229], v209
	ds_read_b128 v[236:239], v209 offset:12800
	ds_read_b128 v[240:243], v209 offset:32
	ds_read_b128 v[244:247], v209 offset:12832
	ds_read_b128 v[248:251], v209 offset:64
	ds_read_b128 v[210:213], v209 offset:12864
	s_waitcnt lgkmcnt(5)
	v_mfma_f32_32x32x16_bf16 v[82:97], v[226:229], v[126:129], 0
	ds_read_b128 v[226:229], v209 offset:96
	s_waitcnt lgkmcnt(5)
	v_mfma_f32_32x32x16_bf16 v[66:81], v[236:239], v[126:129], 0
	ds_read_b128 v[236:239], v209 offset:12896
	s_waitcnt lgkmcnt(5)
	v_mfma_f32_32x32x16_bf16 v[82:97], v[240:243], v[142:145], v[82:97]
	ds_read_b128 v[240:243], v209 offset:128
	s_waitcnt lgkmcnt(5)
	v_mfma_f32_32x32x16_bf16 v[66:81], v[244:247], v[142:145], v[66:81]
	ds_read_b128 v[244:247], v209 offset:12928
	s_waitcnt lgkmcnt(5)
	v_mfma_f32_32x32x16_bf16 v[82:97], v[248:251], v[146:149], v[82:97]
	ds_read_b128 v[248:251], v209 offset:160
	s_waitcnt lgkmcnt(5)
	v_mfma_f32_32x32x16_bf16 v[66:81], v[210:213], v[146:149], v[66:81]
	ds_read_b128 v[210:213], v209 offset:12960
	s_waitcnt lgkmcnt(5)
	v_mfma_f32_32x32x16_bf16 v[82:97], v[226:229], v[150:153], v[82:97]
	ds_read_b128 v[226:229], v209 offset:192
	s_waitcnt lgkmcnt(5)
	v_mfma_f32_32x32x16_bf16 v[66:81], v[236:239], v[150:153], v[66:81]
	ds_read_b128 v[236:239], v209 offset:12992
	s_waitcnt lgkmcnt(5)
	v_mfma_f32_32x32x16_bf16 v[82:97], v[240:243], v[154:157], v[82:97]
	ds_read_b128 v[240:243], v209 offset:224
	s_waitcnt lgkmcnt(5)
	v_mfma_f32_32x32x16_bf16 v[66:81], v[244:247], v[154:157], v[66:81]
	ds_read_b128 v[244:247], v209 offset:13024
	s_waitcnt lgkmcnt(5)
	v_mfma_f32_32x32x16_bf16 v[82:97], v[248:251], v[158:161], v[82:97]
	ds_read_b128 v[248:251], v209 offset:256
	s_waitcnt lgkmcnt(5)
	v_mfma_f32_32x32x16_bf16 v[66:81], v[210:213], v[158:161], v[66:81]
	ds_read_b128 v[210:213], v209 offset:13056
	s_waitcnt lgkmcnt(5)
	v_mfma_f32_32x32x16_bf16 v[82:97], v[226:229], v[162:165], v[82:97]
	ds_read_b128 v[226:229], v209 offset:288
	s_waitcnt lgkmcnt(5)
	v_mfma_f32_32x32x16_bf16 v[66:81], v[236:239], v[162:165], v[66:81]
	ds_read_b128 v[236:239], v209 offset:13088
	s_waitcnt lgkmcnt(5)
	v_mfma_f32_32x32x16_bf16 v[82:97], v[240:243], v[166:169], v[82:97]
	ds_read_b128 v[240:243], v209 offset:320
	s_waitcnt lgkmcnt(5)
	v_mfma_f32_32x32x16_bf16 v[66:81], v[244:247], v[166:169], v[66:81]
	ds_read_b128 v[244:247], v209 offset:13120
	s_waitcnt lgkmcnt(5)
	v_mfma_f32_32x32x16_bf16 v[82:97], v[248:251], v[170:173], v[82:97]
	ds_read_b128 v[248:251], v209 offset:352
	s_waitcnt lgkmcnt(5)
	v_mfma_f32_32x32x16_bf16 v[66:81], v[210:213], v[170:173], v[66:81]
	ds_read_b128 v[210:213], v209 offset:13152
	s_waitcnt lgkmcnt(5)
	v_mfma_f32_32x32x16_bf16 v[82:97], v[226:229], v[174:177], v[82:97]
	s_waitcnt lgkmcnt(4)
	v_mfma_f32_32x32x16_bf16 v[66:81], v[236:239], v[174:177], v[66:81]
	s_waitcnt lgkmcnt(3)
	v_mfma_f32_32x32x16_bf16 v[82:97], v[240:243], v[178:181], v[82:97]
	s_waitcnt lgkmcnt(2)
	v_mfma_f32_32x32x16_bf16 v[66:81], v[244:247], v[178:181], v[66:81]
	s_waitcnt lgkmcnt(1)
	v_mfma_f32_32x32x16_bf16 v[82:97], v[248:251], v[182:185], v[82:97]
	s_waitcnt lgkmcnt(0)
	v_mfma_f32_32x32x16_bf16 v[66:81], v[210:213], v[182:185], v[66:81]
	s_setprio 2
	ds_read_b128 v[236:239], v205 offset:25600
	ds_read_b128 v[240:243], v205 offset:30208
	ds_read_b128 v[244:247], v205 offset:34816
	ds_read_b128 v[248:251], v205 offset:39424
	ds_read_b128 v[210:213], v205 offset:25632
	s_nop 4
	v_max_f32_e32 v186, v83, v83
	v_max_f32_e32 v187, v82, v82
	v_max_f32_e32 v186, v187, v186
	v_max3_f32 v186, v186, v84, v85
	v_max3_f32 v186, v186, v86, v87
	v_max3_f32 v186, v186, v88, v89
	v_max3_f32 v186, v186, v90, v91
	v_max3_f32 v186, v186, v92, v93
	v_max3_f32 v186, v186, v94, v95
	v_max3_f32 v186, v186, v96, v97
	v_max3_f32 v186, v186, v66, v67
	v_max3_f32 v186, v186, v68, v69
	v_max3_f32 v186, v186, v70, v71
	v_max3_f32 v186, v186, v72, v73
	v_max3_f32 v186, v186, v74, v75
	v_max3_f32 v186, v186, v76, v77
	v_max3_f32 v186, v186, v78, v79
	v_max3_f32 v186, v186, v80, v81
	v_mov_b32_e32 v187, v186
	s_nop 1
	v_permlane32_swap_b32_e32 v186, v187
	v_max_f32_e32 v187, v186, v187
	v_add_f32_e32 v186, 0x41380000, v223
	v_cmp_gt_f32_e32 vcc, v187, v186
	s_cbranch_vccz .Latt3_nr_10
	v_max_f32_e32 v186, v187, v187
	v_max_f32_e32 v187, v223, v223
	v_max_f32_e32 v187, v187, v186
	v_sub_f32_e32 v186, v223, v187
	v_exp_f32_e32 v186, v186
	v_mov_b32_e32 v223, v187
	v_pk_mul_f32 v[64:65], v[64:65], v[186:187] op_sel_hi:[1,0]
	v_pk_mul_f32 v[62:63], v[62:63], v[186:187] op_sel_hi:[1,0]
	v_pk_mul_f32 v[60:61], v[60:61], v[186:187] op_sel_hi:[1,0]
	v_pk_mul_f32 v[58:59], v[58:59], v[186:187] op_sel_hi:[1,0]
	v_pk_mul_f32 v[56:57], v[56:57], v[186:187] op_sel_hi:[1,0]
	v_pk_mul_f32 v[54:55], v[54:55], v[186:187] op_sel_hi:[1,0]
	v_pk_mul_f32 v[52:53], v[52:53], v[186:187] op_sel_hi:[1,0]
	v_pk_mul_f32 v[50:51], v[50:51], v[186:187] op_sel_hi:[1,0]
	v_pk_mul_f32 v[48:49], v[48:49], v[186:187] op_sel_hi:[1,0]
	v_pk_mul_f32 v[46:47], v[46:47], v[186:187] op_sel_hi:[1,0]
	v_pk_mul_f32 v[44:45], v[44:45], v[186:187] op_sel_hi:[1,0]
	v_pk_mul_f32 v[42:43], v[42:43], v[186:187] op_sel_hi:[1,0]
	v_pk_mul_f32 v[40:41], v[40:41], v[186:187] op_sel_hi:[1,0]
	v_pk_mul_f32 v[38:39], v[38:39], v[186:187] op_sel_hi:[1,0]
	v_pk_mul_f32 v[36:37], v[36:37], v[186:187] op_sel_hi:[1,0]
	v_pk_mul_f32 v[34:35], v[34:35], v[186:187] op_sel_hi:[1,0]
	v_pk_mul_f32 v[32:33], v[32:33], v[186:187] op_sel_hi:[1,0]
	v_pk_mul_f32 v[30:31], v[30:31], v[186:187] op_sel_hi:[1,0]
	v_pk_mul_f32 v[28:29], v[28:29], v[186:187] op_sel_hi:[1,0]
	v_pk_mul_f32 v[26:27], v[26:27], v[186:187] op_sel_hi:[1,0]
	v_pk_mul_f32 v[24:25], v[24:25], v[186:187] op_sel_hi:[1,0]
	v_pk_mul_f32 v[22:23], v[22:23], v[186:187] op_sel_hi:[1,0]
	v_pk_mul_f32 v[20:21], v[20:21], v[186:187] op_sel_hi:[1,0]
	v_pk_mul_f32 v[18:19], v[18:19], v[186:187] op_sel_hi:[1,0]
	v_pk_mul_f32 v[16:17], v[16:17], v[186:187] op_sel_hi:[1,0]
	v_pk_mul_f32 v[14:15], v[14:15], v[186:187] op_sel_hi:[1,0]
	v_pk_mul_f32 v[12:13], v[12:13], v[186:187] op_sel_hi:[1,0]
	v_pk_mul_f32 v[10:11], v[10:11], v[186:187] op_sel_hi:[1,0]
	v_pk_mul_f32 v[8:9], v[8:9], v[186:187] op_sel_hi:[1,0]
	v_pk_mul_f32 v[6:7], v[6:7], v[186:187] op_sel_hi:[1,0]
	v_pk_mul_f32 v[4:5], v[4:5], v[186:187] op_sel_hi:[1,0]
	v_pk_mul_f32 v[2:3], v[2:3], v[186:187] op_sel_hi:[1,0]
	v_mul_f32_e32 v225, v225, v186
.Latt3_nr_10:
	v_sub_f32_e32 v82, v82, v223
	v_sub_f32_e32 v83, v83, v223
	v_sub_f32_e32 v84, v84, v223
	v_sub_f32_e32 v85, v85, v223
	v_exp_f32_e32 v82, v82
	v_exp_f32_e32 v83, v83
	v_exp_f32_e32 v84, v84
	v_exp_f32_e32 v85, v85
	v_sub_f32_e32 v86, v86, v223
	v_sub_f32_e32 v87, v87, v223
	v_sub_f32_e32 v88, v88, v223
	v_sub_f32_e32 v89, v89, v223
	v_exp_f32_e32 v86, v86
	v_exp_f32_e32 v87, v87
	v_exp_f32_e32 v88, v88
	v_exp_f32_e32 v89, v89
	v_cvt_pk_bf16_f32 v226, v82, v83
	v_cvt_pk_bf16_f32 v227, v84, v85
	v_cvt_pk_bf16_f32 v228, v86, v87
	v_cvt_pk_bf16_f32 v229, v88, v89
	s_nop 1
	s_waitcnt lgkmcnt(4)
	v_mfma_f32_32x32x16_bf16 v[50:65], v[236:239], v[226:229], v[50:65]
	ds_read_b128 v[236:239], v205 offset:30240
	v_sub_f32_e32 v90, v90, v223
	v_sub_f32_e32 v91, v91, v223
	v_sub_f32_e32 v92, v92, v223
	v_sub_f32_e32 v93, v93, v223
	v_exp_f32_e32 v90, v90
	v_exp_f32_e32 v91, v91
	s_waitcnt lgkmcnt(4)
	v_mfma_f32_32x32x16_bf16 v[34:49], v[240:243], v[226:229], v[34:49]
	ds_read_b128 v[240:243], v205 offset:34848
	v_exp_f32_e32 v92, v92
	v_exp_f32_e32 v93, v93
	v_sub_f32_e32 v94, v94, v223
	v_sub_f32_e32 v95, v95, v223
	v_sub_f32_e32 v96, v96, v223
	v_sub_f32_e32 v97, v97, v223
	s_waitcnt lgkmcnt(4)
	v_mfma_f32_32x32x16_bf16 v[18:33], v[244:247], v[226:229], v[18:33]
	ds_read_b128 v[244:247], v205 offset:39456
	v_exp_f32_e32 v94, v94
	v_exp_f32_e32 v95, v95
	v_exp_f32_e32 v96, v96
	v_exp_f32_e32 v97, v97
	v_add_f32_e32 v186, 0, v82
	v_add_f32_e32 v187, 0, v86
	s_waitcnt lgkmcnt(4)
	v_mfma_f32_32x32x16_bf16 v[2:17], v[248:251], v[226:229], v[2:17]
	ds_read_b128 v[248:251], v205 offset:25664
	v_add_f32_e32 v186, v83, v186
	v_add_f32_e32 v187, v87, v187
	v_add_f32_e32 v186, v84, v186
	v_add_f32_e32 v187, v88, v187
	v_add_f32_e32 v186, v85, v186
	v_add_f32_e32 v187, v89, v187
	v_cvt_pk_bf16_f32 v226, v90, v91
	v_cvt_pk_bf16_f32 v227, v92, v93
	v_cvt_pk_bf16_f32 v228, v94, v95
	v_cvt_pk_bf16_f32 v229, v96, v97
	s_nop 1
	s_waitcnt lgkmcnt(4)
	v_mfma_f32_32x32x16_bf16 v[50:65], v[210:213], v[226:229], v[50:65]
	ds_read_b128 v[210:213], v205 offset:30272
	v_sub_f32_e32 v66, v66, v223
	v_sub_f32_e32 v67, v67, v223
	v_sub_f32_e32 v68, v68, v223
	v_sub_f32_e32 v69, v69, v223
	v_exp_f32_e32 v66, v66
	v_exp_f32_e32 v67, v67
	s_waitcnt lgkmcnt(4)
	v_mfma_f32_32x32x16_bf16 v[34:49], v[236:239], v[226:229], v[34:49]
	ds_read_b128 v[236:239], v205 offset:34880
	v_exp_f32_e32 v68, v68
	v_exp_f32_e32 v69, v69
	v_sub_f32_e32 v70, v70, v223
	v_sub_f32_e32 v71, v71, v223
	v_sub_f32_e32 v72, v72, v223
	v_sub_f32_e32 v73, v73, v223
	s_waitcnt lgkmcnt(4)
	v_mfma_f32_32x32x16_bf16 v[18:33], v[240:243], v[226:229], v[18:33]
	ds_read_b128 v[240:243], v205 offset:39488
	v_exp_f32_e32 v70, v70
	v_exp_f32_e32 v71, v71
	v_exp_f32_e32 v72, v72
	v_exp_f32_e32 v73, v73
	v_add_f32_e32 v186, v90, v186
	v_add_f32_e32 v187, v94, v187
	s_waitcnt lgkmcnt(4)
	v_mfma_f32_32x32x16_bf16 v[2:17], v[244:247], v[226:229], v[2:17]
	ds_read_b128 v[244:247], v205 offset:25696
	v_add_f32_e32 v186, v91, v186
	v_add_f32_e32 v187, v95, v187
	v_add_f32_e32 v186, v92, v186
	v_add_f32_e32 v187, v96, v187
	v_add_f32_e32 v186, v93, v186
	v_add_f32_e32 v187, v97, v187
	v_cvt_pk_bf16_f32 v226, v66, v67
	v_cvt_pk_bf16_f32 v227, v68, v69
	v_cvt_pk_bf16_f32 v228, v70, v71
	v_cvt_pk_bf16_f32 v229, v72, v73
	s_nop 1
	s_waitcnt lgkmcnt(4)
	v_mfma_f32_32x32x16_bf16 v[50:65], v[248:251], v[226:229], v[50:65]
	ds_read_b128 v[248:251], v205 offset:30304
	v_sub_f32_e32 v74, v74, v223
	v_sub_f32_e32 v75, v75, v223
	v_sub_f32_e32 v76, v76, v223
	v_sub_f32_e32 v77, v77, v223
	v_exp_f32_e32 v74, v74
	v_exp_f32_e32 v75, v75
	s_waitcnt lgkmcnt(4)
	v_mfma_f32_32x32x16_bf16 v[34:49], v[210:213], v[226:229], v[34:49]
	ds_read_b128 v[210:213], v205 offset:34912
	v_exp_f32_e32 v76, v76
	v_exp_f32_e32 v77, v77
	v_sub_f32_e32 v78, v78, v223
	v_sub_f32_e32 v79, v79, v223
	v_sub_f32_e32 v80, v80, v223
	v_sub_f32_e32 v81, v81, v223
	s_waitcnt lgkmcnt(4)
	v_mfma_f32_32x32x16_bf16 v[18:33], v[236:239], v[226:229], v[18:33]
	ds_read_b128 v[236:239], v205 offset:39520
	v_exp_f32_e32 v78, v78
	v_exp_f32_e32 v79, v79
	v_exp_f32_e32 v80, v80
	v_exp_f32_e32 v81, v81
	v_add_f32_e32 v186, v66, v186
	v_add_f32_e32 v187, v70, v187
	s_waitcnt lgkmcnt(4)
	v_mfma_f32_32x32x16_bf16 v[2:17], v[240:243], v[226:229], v[2:17]
	v_add_f32_e32 v186, v67, v186
	v_add_f32_e32 v187, v71, v187
	v_add_f32_e32 v186, v68, v186
	v_add_f32_e32 v187, v72, v187
	v_add_f32_e32 v186, v69, v186
	v_add_f32_e32 v187, v73, v187
	v_cvt_pk_bf16_f32 v226, v74, v75
	v_cvt_pk_bf16_f32 v227, v76, v77
	v_cvt_pk_bf16_f32 v228, v78, v79
	v_cvt_pk_bf16_f32 v229, v80, v81
	s_nop 1
	s_waitcnt lgkmcnt(3)
	v_mfma_f32_32x32x16_bf16 v[50:65], v[244:247], v[226:229], v[50:65]
	v_add_f32_e32 v186, v74, v186
	v_add_f32_e32 v187, v78, v187
	s_waitcnt lgkmcnt(2)
	v_mfma_f32_32x32x16_bf16 v[34:49], v[248:251], v[226:229], v[34:49]
	v_add_f32_e32 v186, v75, v186
	v_add_f32_e32 v187, v79, v187
	s_waitcnt lgkmcnt(1)
	v_mfma_f32_32x32x16_bf16 v[18:33], v[210:213], v[226:229], v[18:33]
	v_add_f32_e32 v186, v76, v186
	v_add_f32_e32 v187, v80, v187
	s_waitcnt lgkmcnt(0)
	s_barrier
	v_mfma_f32_32x32x16_bf16 v[2:17], v[236:239], v[226:229], v[2:17]
	v_add_f32_e32 v186, v77, v186
	v_add_f32_e32 v187, v81, v187
	v_add_f32_e32 v186, v186, v187
	v_add_f32_e32 v224, v225, v186
	s_setprio 0
	s_add_i32 s13, s11, 2
	s_cmp_ge_u32 s13, s5
	s_cbranch_scc1 .Latt3_wskip_11
	v_add_u32_e32 v206, s72, v219
	v_add_u32_e32 v208, s72, v220
	v_add_u32_e32 v186, s72, v221
	v_add_u32_e32 v187, s72, v222
	s_add_i32 s13, s11, 3
	s_cmp_ge_u32 s13, s5
	s_cbranch_scc1 .Latt3_wtail_12
	s_waitcnt vmcnt(9)
	ds_write_b128 v206, v[102:105]
	s_waitcnt vmcnt(8)
	ds_write_b128 v208, v[106:109]
	s_waitcnt vmcnt(7)
	ds_write_b128 v186, v[114:117]
	s_waitcnt vmcnt(6)
	ds_write_b128 v187, v[98:101] offset:25600
	s_waitcnt vmcnt(5)
	ds_write_b128 v187, v[110:113] offset:34816
	s_branch .Latt3_wld_13

.Latt3_B_loop:
	v_add_u32_e32 v209, s70, v215
	v_add_u32_e32 v205, s70, v216
	ds_read_b128 v[226:229], v209
	ds_read_b128 v[236:239], v209 offset:12800
	ds_read_b128 v[240:243], v209 offset:32
	ds_read_b128 v[244:247], v209 offset:12832
	ds_read_b128 v[248:251], v209 offset:64
	ds_read_b128 v[210:213], v209 offset:12864
	s_waitcnt lgkmcnt(5)
	v_mfma_f32_32x32x16_bf16 v[82:97], v[226:229], v[126:129], 0
	ds_read_b128 v[226:229], v209 offset:96
	s_waitcnt lgkmcnt(5)
	v_mfma_f32_32x32x16_bf16 v[66:81], v[236:239], v[126:129], 0
	ds_read_b128 v[236:239], v209 offset:12896
	s_waitcnt lgkmcnt(5)
	v_mfma_f32_32x32x16_bf16 v[82:97], v[240:243], v[142:145], v[82:97]
	ds_read_b128 v[240:243], v209 offset:128
	s_waitcnt lgkmcnt(5)
	v_mfma_f32_32x32x16_bf16 v[66:81], v[244:247], v[142:145], v[66:81]
	ds_read_b128 v[244:247], v209 offset:12928
	s_waitcnt lgkmcnt(5)
	v_mfma_f32_32x32x16_bf16 v[82:97], v[248:251], v[146:149], v[82:97]
	ds_read_b128 v[248:251], v209 offset:160
	s_waitcnt lgkmcnt(5)
	v_mfma_f32_32x32x16_bf16 v[66:81], v[210:213], v[146:149], v[66:81]
	ds_read_b128 v[210:213], v209 offset:12960
	s_waitcnt lgkmcnt(5)
	v_mfma_f32_32x32x16_bf16 v[82:97], v[226:229], v[150:153], v[82:97]
	ds_read_b128 v[226:229], v209 offset:192
	s_waitcnt lgkmcnt(5)
	v_mfma_f32_32x32x16_bf16 v[66:81], v[236:239], v[150:153], v[66:81]
	ds_read_b128 v[236:239], v209 offset:12992
	s_waitcnt lgkmcnt(5)
	v_mfma_f32_32x32x16_bf16 v[82:97], v[240:243], v[154:157], v[82:97]
	ds_read_b128 v[240:243], v209 offset:224
	s_waitcnt lgkmcnt(5)
	v_mfma_f32_32x32x16_bf16 v[66:81], v[244:247], v[154:157], v[66:81]
	ds_read_b128 v[244:247], v209 offset:13024
	s_waitcnt lgkmcnt(5)
	v_mfma_f32_32x32x16_bf16 v[82:97], v[248:251], v[158:161], v[82:97]
	ds_read_b128 v[248:251], v209 offset:256
	s_waitcnt lgkmcnt(5)
	v_mfma_f32_32x32x16_bf16 v[66:81], v[210:213], v[158:161], v[66:81]
	ds_read_b128 v[210:213], v209 offset:13056
	s_waitcnt lgkmcnt(5)
	v_mfma_f32_32x32x16_bf16 v[82:97], v[226:229], v[162:165], v[82:97]
	ds_read_b128 v[226:229], v209 offset:288
	s_waitcnt lgkmcnt(5)
	v_mfma_f32_32x32x16_bf16 v[66:81], v[236:239], v[162:165], v[66:81]
	ds_read_b128 v[236:239], v209 offset:13088
	s_waitcnt lgkmcnt(5)
	v_mfma_f32_32x32x16_bf16 v[82:97], v[240:243], v[166:169], v[82:97]
	ds_read_b128 v[240:243], v209 offset:320
	s_waitcnt lgkmcnt(5)
	v_mfma_f32_32x32x16_bf16 v[66:81], v[244:247], v[166:169], v[66:81]
	ds_read_b128 v[244:247], v209 offset:13120
	s_waitcnt lgkmcnt(5)
	v_mfma_f32_32x32x16_bf16 v[82:97], v[248:251], v[170:173], v[82:97]
	ds_read_b128 v[248:251], v209 offset:352
	s_waitcnt lgkmcnt(5)
	v_mfma_f32_32x32x16_bf16 v[66:81], v[210:213], v[170:173], v[66:81]
	ds_read_b128 v[210:213], v209 offset:13152
	s_waitcnt lgkmcnt(5)
	v_mfma_f32_32x32x16_bf16 v[82:97], v[226:229], v[174:177], v[82:97]
	s_waitcnt lgkmcnt(4)
	v_mfma_f32_32x32x16_bf16 v[66:81], v[236:239], v[174:177], v[66:81]
	s_waitcnt lgkmcnt(3)
	v_mfma_f32_32x32x16_bf16 v[82:97], v[240:243], v[178:181], v[82:97]
	s_waitcnt lgkmcnt(2)
	v_mfma_f32_32x32x16_bf16 v[66:81], v[244:247], v[178:181], v[66:81]
	s_waitcnt lgkmcnt(1)
	v_mfma_f32_32x32x16_bf16 v[82:97], v[248:251], v[182:185], v[82:97]
	s_waitcnt lgkmcnt(0)
	s_barrier
	v_mfma_f32_32x32x16_bf16 v[66:81], v[210:213], v[182:185], v[66:81]
	s_setprio 2
	ds_read_b128 v[236:239], v205 offset:25600
	ds_read_b128 v[240:243], v205 offset:30208
	ds_read_b128 v[244:247], v205 offset:34816
	ds_read_b128 v[248:251], v205 offset:39424
	ds_read_b128 v[210:213], v205 offset:25632
	s_nop 4
	v_max_f32_e32 v186, v83, v83
	v_max_f32_e32 v187, v82, v82
	v_max_f32_e32 v186, v187, v186
	v_max3_f32 v186, v186, v84, v85
	v_max3_f32 v186, v186, v86, v87
	v_max3_f32 v186, v186, v88, v89
	v_max3_f32 v186, v186, v90, v91
	v_max3_f32 v186, v186, v92, v93
	v_max3_f32 v186, v186, v94, v95
	v_max3_f32 v186, v186, v96, v97
	v_max3_f32 v186, v186, v66, v67
	v_max3_f32 v186, v186, v68, v69
	v_max3_f32 v186, v186, v70, v71
	v_max3_f32 v186, v186, v72, v73
	v_max3_f32 v186, v186, v74, v75
	v_max3_f32 v186, v186, v76, v77
	v_max3_f32 v186, v186, v78, v79
	v_max3_f32 v186, v186, v80, v81
	v_mov_b32_e32 v187, v186
	s_nop 1
	v_permlane32_swap_b32_e32 v186, v187
	v_max_f32_e32 v187, v186, v187
	v_add_f32_e32 v186, 0x41380000, v223
	v_cmp_gt_f32_e32 vcc, v187, v186
	s_cbranch_vccz .Latt3_nr_15
	v_max_f32_e32 v186, v187, v187
	v_max_f32_e32 v187, v223, v223
	v_max_f32_e32 v187, v187, v186
	v_sub_f32_e32 v186, v223, v187
	v_exp_f32_e32 v186, v186
	v_mov_b32_e32 v223, v187
	v_pk_mul_f32 v[64:65], v[64:65], v[186:187] op_sel_hi:[1,0]
	v_pk_mul_f32 v[62:63], v[62:63], v[186:187] op_sel_hi:[1,0]
	v_pk_mul_f32 v[60:61], v[60:61], v[186:187] op_sel_hi:[1,0]
	v_pk_mul_f32 v[58:59], v[58:59], v[186:187] op_sel_hi:[1,0]
	v_pk_mul_f32 v[56:57], v[56:57], v[186:187] op_sel_hi:[1,0]
	v_pk_mul_f32 v[54:55], v[54:55], v[186:187] op_sel_hi:[1,0]
	v_pk_mul_f32 v[52:53], v[52:53], v[186:187] op_sel_hi:[1,0]
	v_pk_mul_f32 v[50:51], v[50:51], v[186:187] op_sel_hi:[1,0]
	v_pk_mul_f32 v[48:49], v[48:49], v[186:187] op_sel_hi:[1,0]
	v_pk_mul_f32 v[46:47], v[46:47], v[186:187] op_sel_hi:[1,0]
	v_pk_mul_f32 v[44:45], v[44:45], v[186:187] op_sel_hi:[1,0]
	v_pk_mul_f32 v[42:43], v[42:43], v[186:187] op_sel_hi:[1,0]
	v_pk_mul_f32 v[40:41], v[40:41], v[186:187] op_sel_hi:[1,0]
	v_pk_mul_f32 v[38:39], v[38:39], v[186:187] op_sel_hi:[1,0]
	v_pk_mul_f32 v[36:37], v[36:37], v[186:187] op_sel_hi:[1,0]
	v_pk_mul_f32 v[34:35], v[34:35], v[186:187] op_sel_hi:[1,0]
	v_pk_mul_f32 v[32:33], v[32:33], v[186:187] op_sel_hi:[1,0]
	v_pk_mul_f32 v[30:31], v[30:31], v[186:187] op_sel_hi:[1,0]
	v_pk_mul_f32 v[28:29], v[28:29], v[186:187] op_sel_hi:[1,0]
	v_pk_mul_f32 v[26:27], v[26:27], v[186:187] op_sel_hi:[1,0]
	v_pk_mul_f32 v[24:25], v[24:25], v[186:187] op_sel_hi:[1,0]
	v_pk_mul_f32 v[22:23], v[22:23], v[186:187] op_sel_hi:[1,0]
	v_pk_mul_f32 v[20:21], v[20:21], v[186:187] op_sel_hi:[1,0]
	v_pk_mul_f32 v[18:19], v[18:19], v[186:187] op_sel_hi:[1,0]
	v_pk_mul_f32 v[16:17], v[16:17], v[186:187] op_sel_hi:[1,0]
	v_pk_mul_f32 v[14:15], v[14:15], v[186:187] op_sel_hi:[1,0]
	v_pk_mul_f32 v[12:13], v[12:13], v[186:187] op_sel_hi:[1,0]
	v_pk_mul_f32 v[10:11], v[10:11], v[186:187] op_sel_hi:[1,0]
	v_pk_mul_f32 v[8:9], v[8:9], v[186:187] op_sel_hi:[1,0]
	v_pk_mul_f32 v[6:7], v[6:7], v[186:187] op_sel_hi:[1,0]
	v_pk_mul_f32 v[4:5], v[4:5], v[186:187] op_sel_hi:[1,0]
	v_pk_mul_f32 v[2:3], v[2:3], v[186:187] op_sel_hi:[1,0]
	v_mul_f32_e32 v224, v224, v186
.Latt3_nr_15:
	v_sub_f32_e32 v82, v82, v223
	v_sub_f32_e32 v83, v83, v223
	v_sub_f32_e32 v84, v84, v223
	v_sub_f32_e32 v85, v85, v223
	v_exp_f32_e32 v82, v82
	v_exp_f32_e32 v83, v83
	v_exp_f32_e32 v84, v84
	v_exp_f32_e32 v85, v85
	v_sub_f32_e32 v86, v86, v223
	v_sub_f32_e32 v87, v87, v223
	v_sub_f32_e32 v88, v88, v223
	v_sub_f32_e32 v89, v89, v223
	v_exp_f32_e32 v86, v86
	v_exp_f32_e32 v87, v87
	v_exp_f32_e32 v88, v88
	v_exp_f32_e32 v89, v89
	v_cvt_pk_bf16_f32 v226, v82, v83
	v_cvt_pk_bf16_f32 v227, v84, v85
	v_cvt_pk_bf16_f32 v228, v86, v87
	v_cvt_pk_bf16_f32 v229, v88, v89
	s_nop 1
	s_waitcnt lgkmcnt(4)
	v_mfma_f32_32x32x16_bf16 v[50:65], v[236:239], v[226:229], v[50:65]
	ds_read_b128 v[236:239], v205 offset:30240
	v_sub_f32_e32 v90, v90, v223
	v_sub_f32_e32 v91, v91, v223
	v_sub_f32_e32 v92, v92, v223
	v_sub_f32_e32 v93, v93, v223
	v_exp_f32_e32 v90, v90
	v_exp_f32_e32 v91, v91
	s_waitcnt lgkmcnt(4)
	v_mfma_f32_32x32x16_bf16 v[34:49], v[240:243], v[226:229], v[34:49]
	ds_read_b128 v[240:243], v205 offset:34848
	v_exp_f32_e32 v92, v92
	v_exp_f32_e32 v93, v93
	v_sub_f32_e32 v94, v94, v223
	v_sub_f32_e32 v95, v95, v223
	v_sub_f32_e32 v96, v96, v223
	v_sub_f32_e32 v97, v97, v223
	s_waitcnt lgkmcnt(4)
	v_mfma_f32_32x32x16_bf16 v[18:33], v[244:247], v[226:229], v[18:33]
	ds_read_b128 v[244:247], v205 offset:39456
	v_exp_f32_e32 v94, v94
	v_exp_f32_e32 v95, v95
	v_exp_f32_e32 v96, v96
	v_exp_f32_e32 v97, v97
	v_add_f32_e32 v186, 0, v82
	v_add_f32_e32 v187, 0, v86
	s_waitcnt lgkmcnt(4)
	v_mfma_f32_32x32x16_bf16 v[2:17], v[248:251], v[226:229], v[2:17]
	ds_read_b128 v[248:251], v205 offset:25664
	v_add_f32_e32 v186, v83, v186
	v_add_f32_e32 v187, v87, v187
	v_add_f32_e32 v186, v84, v186
	v_add_f32_e32 v187, v88, v187
	v_add_f32_e32 v186, v85, v186
	v_add_f32_e32 v187, v89, v187
	v_cvt_pk_bf16_f32 v226, v90, v91
	v_cvt_pk_bf16_f32 v227, v92, v93
	v_cvt_pk_bf16_f32 v228, v94, v95
	v_cvt_pk_bf16_f32 v229, v96, v97
	s_nop 1
	s_waitcnt lgkmcnt(4)
	v_mfma_f32_32x32x16_bf16 v[50:65], v[210:213], v[226:229], v[50:65]
	ds_read_b128 v[210:213], v205 offset:30272
	v_sub_f32_e32 v66, v66, v223
	v_sub_f32_e32 v67, v67, v223
	v_sub_f32_e32 v68, v68, v223
	v_sub_f32_e32 v69, v69, v223
	v_exp_f32_e32 v66, v66
	v_exp_f32_e32 v67, v67
	s_waitcnt lgkmcnt(4)
	v_mfma_f32_32x32x16_bf16 v[34:49], v[236:239], v[226:229], v[34:49]
	ds_read_b128 v[236:239], v205 offset:34880
	v_exp_f32_e32 v68, v68
	v_exp_f32_e32 v69, v69
	v_sub_f32_e32 v70, v70, v223
	v_sub_f32_e32 v71, v71, v223
	v_sub_f32_e32 v72, v72, v223
	v_sub_f32_e32 v73, v73, v223
	s_waitcnt lgkmcnt(4)
	v_mfma_f32_32x32x16_bf16 v[18:33], v[240:243], v[226:229], v[18:33]
	ds_read_b128 v[240:243], v205 offset:39488
	v_exp_f32_e32 v70, v70
	v_exp_f32_e32 v71, v71
	v_exp_f32_e32 v72, v72
	v_exp_f32_e32 v73, v73
	v_add_f32_e32 v186, v90, v186
	v_add_f32_e32 v187, v94, v187
	s_waitcnt lgkmcnt(4)
	v_mfma_f32_32x32x16_bf16 v[2:17], v[244:247], v[226:229], v[2:17]
	ds_read_b128 v[244:247], v205 offset:25696
	v_add_f32_e32 v186, v91, v186
	v_add_f32_e32 v187, v95, v187
	v_add_f32_e32 v186, v92, v186
	v_add_f32_e32 v187, v96, v187
	v_add_f32_e32 v186, v93, v186
	v_add_f32_e32 v187, v97, v187
	v_cvt_pk_bf16_f32 v226, v66, v67
	v_cvt_pk_bf16_f32 v227, v68, v69
	v_cvt_pk_bf16_f32 v228, v70, v71
	v_cvt_pk_bf16_f32 v229, v72, v73
	s_nop 1
	s_waitcnt lgkmcnt(4)
	v_mfma_f32_32x32x16_bf16 v[50:65], v[248:251], v[226:229], v[50:65]
	ds_read_b128 v[248:251], v205 offset:30304
	v_sub_f32_e32 v74, v74, v223
	v_sub_f32_e32 v75, v75, v223
	v_sub_f32_e32 v76, v76, v223
	v_sub_f32_e32 v77, v77, v223
	v_exp_f32_e32 v74, v74
	v_exp_f32_e32 v75, v75
	s_waitcnt lgkmcnt(4)
	v_mfma_f32_32x32x16_bf16 v[34:49], v[210:213], v[226:229], v[34:49]
	ds_read_b128 v[210:213], v205 offset:34912
	v_exp_f32_e32 v76, v76
	v_exp_f32_e32 v77, v77
	v_sub_f32_e32 v78, v78, v223
	v_sub_f32_e32 v79, v79, v223
	v_sub_f32_e32 v80, v80, v223
	v_sub_f32_e32 v81, v81, v223
	s_waitcnt lgkmcnt(4)
	v_mfma_f32_32x32x16_bf16 v[18:33], v[236:239], v[226:229], v[18:33]
	ds_read_b128 v[236:239], v205 offset:39520
	v_exp_f32_e32 v78, v78
	v_exp_f32_e32 v79, v79
	v_exp_f32_e32 v80, v80
	v_exp_f32_e32 v81, v81
	v_add_f32_e32 v186, v66, v186
	v_add_f32_e32 v187, v70, v187
	s_waitcnt lgkmcnt(4)
	v_mfma_f32_32x32x16_bf16 v[2:17], v[240:243], v[226:229], v[2:17]
	v_add_f32_e32 v186, v67, v186
	v_add_f32_e32 v187, v71, v187
	v_add_f32_e32 v186, v68, v186
	v_add_f32_e32 v187, v72, v187
	v_add_f32_e32 v186, v69, v186
	v_add_f32_e32 v187, v73, v187
	v_cvt_pk_bf16_f32 v226, v74, v75
	v_cvt_pk_bf16_f32 v227, v76, v77
	v_cvt_pk_bf16_f32 v228, v78, v79
	v_cvt_pk_bf16_f32 v229, v80, v81
	s_nop 1
	s_waitcnt lgkmcnt(3)
	v_mfma_f32_32x32x16_bf16 v[50:65], v[244:247], v[226:229], v[50:65]
	v_add_f32_e32 v186, v74, v186
	v_add_f32_e32 v187, v78, v187
	s_waitcnt lgkmcnt(2)
	v_mfma_f32_32x32x16_bf16 v[34:49], v[248:251], v[226:229], v[34:49]
	v_add_f32_e32 v186, v75, v186
	v_add_f32_e32 v187, v79, v187
	s_waitcnt lgkmcnt(1)
	v_mfma_f32_32x32x16_bf16 v[18:33], v[210:213], v[226:229], v[18:33]
	v_add_f32_e32 v186, v76, v186
	v_add_f32_e32 v187, v80, v187
	s_waitcnt lgkmcnt(0)
	v_mfma_f32_32x32x16_bf16 v[2:17], v[236:239], v[226:229], v[2:17]
	v_add_f32_e32 v186, v77, v186
	v_add_f32_e32 v187, v81, v187
	v_add_f32_e32 v186, v186, v187
	v_add_f32_e32 v225, v224, v186
	s_setprio 0
	s_add_i32 s13, s11, 2
	s_cmp_ge_u32 s13, s5
	s_cbranch_scc1 .Latt3_wskip_16
	v_add_u32_e32 v206, s72, v219
	v_add_u32_e32 v208, s72, v220
	v_add_u32_e32 v186, s72, v221
	v_add_u32_e32 v187, s72, v222
	s_add_i32 s13, s11, 3
	s_cmp_ge_u32 s13, s5
	s_cbranch_scc1 .Latt3_wtail_17
	s_waitcnt vmcnt(9)
	ds_write_b128 v206, v[118:121]
	s_waitcnt vmcnt(8)
	ds_write_b128 v208, v[122:125]
	s_waitcnt vmcnt(7)
	ds_write_b128 v186, v[130:133]
	s_waitcnt vmcnt(6)
	ds_write_b128 v187, v[134:137] offset:25600
	s_waitcnt vmcnt(5)
	ds_write_b128 v187, v[138:141] offset:34816
	s_branch .Latt3_wld_18

.Latt3_wdone_19:
.Latt3_wskip_16:
	s_mov_b32 s13, s70
	s_mov_b32 s70, s71
	s_mov_b32 s71, s72
	s_mov_b32 s72, s13
	s_add_i32 s11, s11, 1
	v_add_u32_e32 v209, s70, v215
	v_add_u32_e32 v205, s70, v216
	ds_read_b128 v[226:229], v209
	ds_read_b128 v[236:239], v209 offset:12800
	ds_read_b128 v[240:243], v209 offset:32
	ds_read_b128 v[244:247], v209 offset:12832
	ds_read_b128 v[248:251], v209 offset:64
	ds_read_b128 v[210:213], v209 offset:12864
	s_waitcnt lgkmcnt(5)
	v_mfma_f32_32x32x16_bf16 v[82:97], v[226:229], v[126:129], 0
	ds_read_b128 v[226:229], v209 offset:96
	s_waitcnt lgkmcnt(5)
	v_mfma_f32_32x32x16_bf16 v[66:81], v[236:239], v[126:129], 0
	ds_read_b128 v[236:239], v209 offset:12896
	s_waitcnt lgkmcnt(5)
	v_mfma_f32_32x32x16_bf16 v[82:97], v[240:243], v[142:145], v[82:97]
	ds_read_b128 v[240:243], v209 offset:128
	s_waitcnt lgkmcnt(5)
	v_mfma_f32_32x32x16_bf16 v[66:81], v[244:247], v[142:145], v[66:81]
	ds_read_b128 v[244:247], v209 offset:12928
	s_waitcnt lgkmcnt(5)
	v_mfma_f32_32x32x16_bf16 v[82:97], v[248:251], v[146:149], v[82:97]
	ds_read_b128 v[248:251], v209 offset:160
	s_waitcnt lgkmcnt(5)
	v_mfma_f32_32x32x16_bf16 v[66:81], v[210:213], v[146:149], v[66:81]
	ds_read_b128 v[210:213], v209 offset:12960
	s_waitcnt lgkmcnt(5)
	v_mfma_f32_32x32x16_bf16 v[82:97], v[226:229], v[150:153], v[82:97]
	ds_read_b128 v[226:229], v209 offset:192
	s_waitcnt lgkmcnt(5)
	v_mfma_f32_32x32x16_bf16 v[66:81], v[236:239], v[150:153], v[66:81]
	ds_read_b128 v[236:239], v209 offset:12992
	s_waitcnt lgkmcnt(5)
	v_mfma_f32_32x32x16_bf16 v[82:97], v[240:243], v[154:157], v[82:97]
	ds_read_b128 v[240:243], v209 offset:224
	s_waitcnt lgkmcnt(5)
	v_mfma_f32_32x32x16_bf16 v[66:81], v[244:247], v[154:157], v[66:81]
	ds_read_b128 v[244:247], v209 offset:13024
	s_waitcnt lgkmcnt(5)
	v_mfma_f32_32x32x16_bf16 v[82:97], v[248:251], v[158:161], v[82:97]
	ds_read_b128 v[248:251], v209 offset:256
	s_waitcnt lgkmcnt(5)
	v_mfma_f32_32x32x16_bf16 v[66:81], v[210:213], v[158:161], v[66:81]
	ds_read_b128 v[210:213], v209 offset:13056
	s_waitcnt lgkmcnt(5)
	v_mfma_f32_32x32x16_bf16 v[82:97], v[226:229], v[162:165], v[82:97]
	ds_read_b128 v[226:229], v209 offset:288
	s_waitcnt lgkmcnt(5)
	v_mfma_f32_32x32x16_bf16 v[66:81], v[236:239], v[162:165], v[66:81]
	ds_read_b128 v[236:239], v209 offset:13088
	s_waitcnt lgkmcnt(5)
	v_mfma_f32_32x32x16_bf16 v[82:97], v[240:243], v[166:169], v[82:97]
	ds_read_b128 v[240:243], v209 offset:320
	s_waitcnt lgkmcnt(5)
	v_mfma_f32_32x32x16_bf16 v[66:81], v[244:247], v[166:169], v[66:81]
	ds_read_b128 v[244:247], v209 offset:13120
	s_waitcnt lgkmcnt(5)
	v_mfma_f32_32x32x16_bf16 v[82:97], v[248:251], v[170:173], v[82:97]
	ds_read_b128 v[248:251], v209 offset:352
	s_waitcnt lgkmcnt(5)
	v_mfma_f32_32x32x16_bf16 v[66:81], v[210:213], v[170:173], v[66:81]
	ds_read_b128 v[210:213], v209 offset:13152
	s_waitcnt lgkmcnt(5)
	v_mfma_f32_32x32x16_bf16 v[82:97], v[226:229], v[174:177], v[82:97]
	s_waitcnt lgkmcnt(4)
	v_mfma_f32_32x32x16_bf16 v[66:81], v[236:239], v[174:177], v[66:81]
	s_waitcnt lgkmcnt(3)
	v_mfma_f32_32x32x16_bf16 v[82:97], v[240:243], v[178:181], v[82:97]
	s_waitcnt lgkmcnt(2)
	v_mfma_f32_32x32x16_bf16 v[66:81], v[244:247], v[178:181], v[66:81]
	s_waitcnt lgkmcnt(1)
	v_mfma_f32_32x32x16_bf16 v[82:97], v[248:251], v[182:185], v[82:97]
	s_waitcnt lgkmcnt(0)
	s_barrier
	v_mfma_f32_32x32x16_bf16 v[66:81], v[210:213], v[182:185], v[66:81]
	s_setprio 2
	ds_read_b128 v[236:239], v205 offset:25600
	ds_read_b128 v[240:243], v205 offset:30208
	ds_read_b128 v[244:247], v205 offset:34816
	ds_read_b128 v[248:251], v205 offset:39424
	ds_read_b128 v[210:213], v205 offset:25632
	s_nop 4
	v_max_f32_e32 v186, v83, v83
	v_max_f32_e32 v187, v82, v82
	v_max_f32_e32 v186, v187, v186
	v_max3_f32 v186, v186, v84, v85
	v_max3_f32 v186, v186, v86, v87
	v_max3_f32 v186, v186, v88, v89
	v_max3_f32 v186, v186, v90, v91
	v_max3_f32 v186, v186, v92, v93
	v_max3_f32 v186, v186, v94, v95
	v_max3_f32 v186, v186, v96, v97
	v_max3_f32 v186, v186, v66, v67
	v_max3_f32 v186, v186, v68, v69
	v_max3_f32 v186, v186, v70, v71
	v_max3_f32 v186, v186, v72, v73
	v_max3_f32 v186, v186, v74, v75
	v_max3_f32 v186, v186, v76, v77
	v_max3_f32 v186, v186, v78, v79
	v_max3_f32 v186, v186, v80, v81
	v_mov_b32_e32 v187, v186
	s_nop 1
	v_permlane32_swap_b32_e32 v186, v187
	v_max_f32_e32 v187, v186, v187
	v_add_f32_e32 v186, 0x41380000, v223
	v_cmp_gt_f32_e32 vcc, v187, v186
	s_cbranch_vccz .Latt3_nr_20
	v_max_f32_e32 v186, v187, v187
	v_max_f32_e32 v187, v223, v223
	v_max_f32_e32 v187, v187, v186
	v_sub_f32_e32 v186, v223, v187
	v_exp_f32_e32 v186, v186
	v_mov_b32_e32 v223, v187
	v_pk_mul_f32 v[64:65], v[64:65], v[186:187] op_sel_hi:[1,0]
	v_pk_mul_f32 v[62:63], v[62:63], v[186:187] op_sel_hi:[1,0]
	v_pk_mul_f32 v[60:61], v[60:61], v[186:187] op_sel_hi:[1,0]
	v_pk_mul_f32 v[58:59], v[58:59], v[186:187] op_sel_hi:[1,0]
	v_pk_mul_f32 v[56:57], v[56:57], v[186:187] op_sel_hi:[1,0]
	v_pk_mul_f32 v[54:55], v[54:55], v[186:187] op_sel_hi:[1,0]
	v_pk_mul_f32 v[52:53], v[52:53], v[186:187] op_sel_hi:[1,0]
	v_pk_mul_f32 v[50:51], v[50:51], v[186:187] op_sel_hi:[1,0]
	v_pk_mul_f32 v[48:49], v[48:49], v[186:187] op_sel_hi:[1,0]
	v_pk_mul_f32 v[46:47], v[46:47], v[186:187] op_sel_hi:[1,0]
	v_pk_mul_f32 v[44:45], v[44:45], v[186:187] op_sel_hi:[1,0]
	v_pk_mul_f32 v[42:43], v[42:43], v[186:187] op_sel_hi:[1,0]
	v_pk_mul_f32 v[40:41], v[40:41], v[186:187] op_sel_hi:[1,0]
	v_pk_mul_f32 v[38:39], v[38:39], v[186:187] op_sel_hi:[1,0]
	v_pk_mul_f32 v[36:37], v[36:37], v[186:187] op_sel_hi:[1,0]
	v_pk_mul_f32 v[34:35], v[34:35], v[186:187] op_sel_hi:[1,0]
	v_pk_mul_f32 v[32:33], v[32:33], v[186:187] op_sel_hi:[1,0]
	v_pk_mul_f32 v[30:31], v[30:31], v[186:187] op_sel_hi:[1,0]
	v_pk_mul_f32 v[28:29], v[28:29], v[186:187] op_sel_hi:[1,0]
	v_pk_mul_f32 v[26:27], v[26:27], v[186:187] op_sel_hi:[1,0]
	v_pk_mul_f32 v[24:25], v[24:25], v[186:187] op_sel_hi:[1,0]
	v_pk_mul_f32 v[22:23], v[22:23], v[186:187] op_sel_hi:[1,0]
	v_pk_mul_f32 v[20:21], v[20:21], v[186:187] op_sel_hi:[1,0]
	v_pk_mul_f32 v[18:19], v[18:19], v[186:187] op_sel_hi:[1,0]
	v_pk_mul_f32 v[16:17], v[16:17], v[186:187] op_sel_hi:[1,0]
	v_pk_mul_f32 v[14:15], v[14:15], v[186:187] op_sel_hi:[1,0]
	v_pk_mul_f32 v[12:13], v[12:13], v[186:187] op_sel_hi:[1,0]
	v_pk_mul_f32 v[10:11], v[10:11], v[186:187] op_sel_hi:[1,0]
	v_pk_mul_f32 v[8:9], v[8:9], v[186:187] op_sel_hi:[1,0]
	v_pk_mul_f32 v[6:7], v[6:7], v[186:187] op_sel_hi:[1,0]
	v_pk_mul_f32 v[4:5], v[4:5], v[186:187] op_sel_hi:[1,0]
	v_pk_mul_f32 v[2:3], v[2:3], v[186:187] op_sel_hi:[1,0]
	v_mul_f32_e32 v225, v225, v186
.Latt3_nr_20:
	v_sub_f32_e32 v82, v82, v223
	v_sub_f32_e32 v83, v83, v223
	v_sub_f32_e32 v84, v84, v223
	v_sub_f32_e32 v85, v85, v223
	v_exp_f32_e32 v82, v82
	v_exp_f32_e32 v83, v83
	v_exp_f32_e32 v84, v84
	v_exp_f32_e32 v85, v85
	v_sub_f32_e32 v86, v86, v223
	v_sub_f32_e32 v87, v87, v223
	v_sub_f32_e32 v88, v88, v223
	v_sub_f32_e32 v89, v89, v223
	v_exp_f32_e32 v86, v86
	v_exp_f32_e32 v87, v87
	v_exp_f32_e32 v88, v88
	v_exp_f32_e32 v89, v89
	v_cvt_pk_bf16_f32 v226, v82, v83
	v_cvt_pk_bf16_f32 v227, v84, v85
	v_cvt_pk_bf16_f32 v228, v86, v87
	v_cvt_pk_bf16_f32 v229, v88, v89
	s_nop 1
	s_waitcnt lgkmcnt(4)
	v_mfma_f32_32x32x16_bf16 v[50:65], v[236:239], v[226:229], v[50:65]
	ds_read_b128 v[236:239], v205 offset:30240
	v_sub_f32_e32 v90, v90, v223
	v_sub_f32_e32 v91, v91, v223
	v_sub_f32_e32 v92, v92, v223
	v_sub_f32_e32 v93, v93, v223
	v_exp_f32_e32 v90, v90
	v_exp_f32_e32 v91, v91
	s_waitcnt lgkmcnt(4)
	v_mfma_f32_32x32x16_bf16 v[34:49], v[240:243], v[226:229], v[34:49]
	ds_read_b128 v[240:243], v205 offset:34848
	v_exp_f32_e32 v92, v92
	v_exp_f32_e32 v93, v93
	v_sub_f32_e32 v94, v94, v223
	v_sub_f32_e32 v95, v95, v223
	v_sub_f32_e32 v96, v96, v223
	v_sub_f32_e32 v97, v97, v223
	s_waitcnt lgkmcnt(4)
	v_mfma_f32_32x32x16_bf16 v[18:33], v[244:247], v[226:229], v[18:33]
	ds_read_b128 v[244:247], v205 offset:39456
	v_exp_f32_e32 v94, v94
	v_exp_f32_e32 v95, v95
	v_exp_f32_e32 v96, v96
	v_exp_f32_e32 v97, v97
	v_add_f32_e32 v186, 0, v82
	v_add_f32_e32 v187, 0, v86
	s_waitcnt lgkmcnt(4)
	v_mfma_f32_32x32x16_bf16 v[2:17], v[248:251], v[226:229], v[2:17]
	ds_read_b128 v[248:251], v205 offset:25664
	v_add_f32_e32 v186, v83, v186
	v_add_f32_e32 v187, v87, v187
	v_add_f32_e32 v186, v84, v186
	v_add_f32_e32 v187, v88, v187
	v_add_f32_e32 v186, v85, v186
	v_add_f32_e32 v187, v89, v187
	v_cvt_pk_bf16_f32 v226, v90, v91
	v_cvt_pk_bf16_f32 v227, v92, v93
	v_cvt_pk_bf16_f32 v228, v94, v95
	v_cvt_pk_bf16_f32 v229, v96, v97
	s_nop 1
	s_waitcnt lgkmcnt(4)
	v_mfma_f32_32x32x16_bf16 v[50:65], v[210:213], v[226:229], v[50:65]
	ds_read_b128 v[210:213], v205 offset:30272
	v_sub_f32_e32 v66, v66, v223
	v_sub_f32_e32 v67, v67, v223
	v_sub_f32_e32 v68, v68, v223
	v_sub_f32_e32 v69, v69, v223
	v_exp_f32_e32 v66, v66
	v_exp_f32_e32 v67, v67
	s_waitcnt lgkmcnt(4)
	v_mfma_f32_32x32x16_bf16 v[34:49], v[236:239], v[226:229], v[34:49]
	ds_read_b128 v[236:239], v205 offset:34880
	v_exp_f32_e32 v68, v68
	v_exp_f32_e32 v69, v69
	v_sub_f32_e32 v70, v70, v223
	v_sub_f32_e32 v71, v71, v223
	v_sub_f32_e32 v72, v72, v223
	v_sub_f32_e32 v73, v73, v223
	s_waitcnt lgkmcnt(4)
	v_mfma_f32_32x32x16_bf16 v[18:33], v[240:243], v[226:229], v[18:33]
	ds_read_b128 v[240:243], v205 offset:39488
	v_exp_f32_e32 v70, v70
	v_exp_f32_e32 v71, v71
	v_exp_f32_e32 v72, v72
	v_exp_f32_e32 v73, v73
	v_add_f32_e32 v186, v90, v186
	v_add_f32_e32 v187, v94, v187
	s_waitcnt lgkmcnt(4)
	v_mfma_f32_32x32x16_bf16 v[2:17], v[244:247], v[226:229], v[2:17]
	ds_read_b128 v[244:247], v205 offset:25696
	v_add_f32_e32 v186, v91, v186
	v_add_f32_e32 v187, v95, v187
	v_add_f32_e32 v186, v92, v186
	v_add_f32_e32 v187, v96, v187
	v_add_f32_e32 v186, v93, v186
	v_add_f32_e32 v187, v97, v187
	v_cvt_pk_bf16_f32 v226, v66, v67
	v_cvt_pk_bf16_f32 v227, v68, v69
	v_cvt_pk_bf16_f32 v228, v70, v71
	v_cvt_pk_bf16_f32 v229, v72, v73
	s_nop 1
	s_waitcnt lgkmcnt(4)
	v_mfma_f32_32x32x16_bf16 v[50:65], v[248:251], v[226:229], v[50:65]
	ds_read_b128 v[248:251], v205 offset:30304
	v_sub_f32_e32 v74, v74, v223
	v_sub_f32_e32 v75, v75, v223
	v_sub_f32_e32 v76, v76, v223
	v_sub_f32_e32 v77, v77, v223
	v_exp_f32_e32 v74, v74
	v_exp_f32_e32 v75, v75
	s_waitcnt lgkmcnt(4)
	v_mfma_f32_32x32x16_bf16 v[34:49], v[210:213], v[226:229], v[34:49]
	ds_read_b128 v[210:213], v205 offset:34912
	v_exp_f32_e32 v76, v76
	v_exp_f32_e32 v77, v77
	v_sub_f32_e32 v78, v78, v223
	v_sub_f32_e32 v79, v79, v223
	v_sub_f32_e32 v80, v80, v223
	v_sub_f32_e32 v81, v81, v223
	s_waitcnt lgkmcnt(4)
	v_mfma_f32_32x32x16_bf16 v[18:33], v[236:239], v[226:229], v[18:33]
	ds_read_b128 v[236:239], v205 offset:39520
	v_exp_f32_e32 v78, v78
	v_exp_f32_e32 v79, v79
	v_exp_f32_e32 v80, v80
	v_exp_f32_e32 v81, v81
	v_add_f32_e32 v186, v66, v186
	v_add_f32_e32 v187, v70, v187
	s_waitcnt lgkmcnt(4)
	v_mfma_f32_32x32x16_bf16 v[2:17], v[240:243], v[226:229], v[2:17]
	v_add_f32_e32 v186, v67, v186
	v_add_f32_e32 v187, v71, v187
	v_add_f32_e32 v186, v68, v186
	v_add_f32_e32 v187, v72, v187
	v_add_f32_e32 v186, v69, v186
	v_add_f32_e32 v187, v73, v187
	v_cvt_pk_bf16_f32 v226, v74, v75
	v_cvt_pk_bf16_f32 v227, v76, v77
	v_cvt_pk_bf16_f32 v228, v78, v79
	v_cvt_pk_bf16_f32 v229, v80, v81
	s_nop 1
	s_waitcnt lgkmcnt(3)
	v_mfma_f32_32x32x16_bf16 v[50:65], v[244:247], v[226:229], v[50:65]
	v_add_f32_e32 v186, v74, v186
	v_add_f32_e32 v187, v78, v187
	s_waitcnt lgkmcnt(2)
	v_mfma_f32_32x32x16_bf16 v[34:49], v[248:251], v[226:229], v[34:49]
	v_add_f32_e32 v186, v75, v186
	v_add_f32_e32 v187, v79, v187
	s_waitcnt lgkmcnt(1)
	v_mfma_f32_32x32x16_bf16 v[18:33], v[210:213], v[226:229], v[18:33]
	v_add_f32_e32 v186, v76, v186
	v_add_f32_e32 v187, v80, v187
	s_waitcnt lgkmcnt(0)
	v_mfma_f32_32x32x16_bf16 v[2:17], v[236:239], v[226:229], v[2:17]
	v_add_f32_e32 v186, v77, v186
	v_add_f32_e32 v187, v81, v187
	v_add_f32_e32 v186, v186, v187
	v_add_f32_e32 v224, v225, v186
	s_setprio 0
	s_add_i32 s13, s11, 2
	s_cmp_ge_u32 s13, s5
	s_cbranch_scc1 .Latt3_wskip_21
	v_add_u32_e32 v206, s72, v219
	v_add_u32_e32 v208, s72, v220
	v_add_u32_e32 v186, s72, v221
	v_add_u32_e32 v187, s72, v222
	s_add_i32 s13, s11, 3
	s_cmp_ge_u32 s13, s5
	s_cbranch_scc1 .Latt3_wtail_22
	s_waitcnt vmcnt(9)
	ds_write_b128 v206, v[102:105]
	s_waitcnt vmcnt(8)
	ds_write_b128 v208, v[106:109]
	s_waitcnt vmcnt(7)
	ds_write_b128 v186, v[114:117]
	s_waitcnt vmcnt(6)
	ds_write_b128 v187, v[98:101] offset:25600
	s_waitcnt vmcnt(5)
	ds_write_b128 v187, v[110:113] offset:34816
	s_branch .Latt3_wld_23
